# gate/up GEMM: hand-written SwiGLU epilogue with packed-f32 scaling and +1 (strategy 7, instruction selection), constant row-address steps
# speedup vs baseline: 1.0015x; 1.0005x over previous
.LBB0_1104:
	v_add_u32_e32 v136, s40, v152
	v_ashrrev_i32_e32 v148, 1, v136
	v_and_b32_e32 v148, 0xffffff80, v148
	v_ashrrev_i32_e32 v149, 31, v148
	v_and_b32_e32 v136, 0x7f, v136
	v_lshl_add_u64 v[148:149], v[148:149], 1, s[20:21]
	v_lshlrev_b32_e32 v136, 1, v136
	v_add_u32_e32 v156, s38, v150
	v_mul_u32_u24_e32 v156, 0x1600, v156
	v_add_u32_e32 v136, v136, v156
	s_mov_b32 s100, 0xbfb8aa3b
	s_mov_b32 s101, 0xbfb8aa3b
	s_mov_b32 s99, 0
	v_lshl_add_u64 v[148:149], v[148:149], 0, v[136:137]
	v_pk_mul_f32 v[156:157], v[124:125], s[100:101]
	v_pk_mul_f32 v[158:159], v[126:127], s[100:101]
	v_pk_mul_f32 v[160:161], v[120:121], s[100:101]
	v_pk_mul_f32 v[162:163], v[122:123], s[100:101]
	v_exp_f32_e32 v156, v156
	v_exp_f32_e32 v157, v157
	v_exp_f32_e32 v158, v158
	v_exp_f32_e32 v159, v159
	v_exp_f32_e32 v160, v160
	v_exp_f32_e32 v161, v161
	v_exp_f32_e32 v162, v162
	v_exp_f32_e32 v163, v163
	v_pk_add_f32 v[156:157], v[156:157], 1.0 op_sel_hi:[1,0]
	v_pk_add_f32 v[158:159], v[158:159], 1.0 op_sel_hi:[1,0]
	v_pk_add_f32 v[160:161], v[160:161], 1.0 op_sel_hi:[1,0]
	v_pk_add_f32 v[162:163], v[162:163], 1.0 op_sel_hi:[1,0]
	v_rcp_f32_e32 v156, v156
	v_rcp_f32_e32 v157, v157
	v_rcp_f32_e32 v158, v158
	v_rcp_f32_e32 v159, v159
	v_rcp_f32_e32 v160, v160
	v_rcp_f32_e32 v161, v161
	v_rcp_f32_e32 v162, v162
	v_rcp_f32_e32 v163, v163
	v_pk_mul_f32 v[156:157], v[124:125], v[156:157]
	v_pk_mul_f32 v[158:159], v[126:127], v[158:159]
	v_pk_mul_f32 v[160:161], v[120:121], v[160:161]
	v_pk_mul_f32 v[162:163], v[122:123], v[162:163]
	v_pk_mul_f32 v[156:157], v[156:157], v[116:117]
	v_pk_mul_f32 v[158:159], v[158:159], v[118:119]
	v_pk_mul_f32 v[160:161], v[160:161], v[112:113]
	v_pk_mul_f32 v[162:163], v[162:163], v[114:115]
	v_cvt_pk_bf16_f32 v156, v156, v157
	v_cvt_pk_bf16_f32 v157, v158, v159
	v_cvt_pk_bf16_f32 v158, v160, v161
	v_cvt_pk_bf16_f32 v159, v162, v163
	global_store_dwordx4 v[148:149], v[156:159], off nt
	s_mov_b32 s98, 0x16000
	v_lshl_add_u64 v[172:173], v[148:149], 0, s[98:99]
	v_pk_mul_f32 v[164:165], v[108:109], s[100:101]
	v_pk_mul_f32 v[166:167], v[110:111], s[100:101]
	v_pk_mul_f32 v[168:169], v[104:105], s[100:101]
	v_pk_mul_f32 v[170:171], v[106:107], s[100:101]
	v_exp_f32_e32 v164, v164
	v_exp_f32_e32 v165, v165
	v_exp_f32_e32 v166, v166
	v_exp_f32_e32 v167, v167
	v_exp_f32_e32 v168, v168
	v_exp_f32_e32 v169, v169
	v_exp_f32_e32 v170, v170
	v_exp_f32_e32 v171, v171
	v_pk_add_f32 v[164:165], v[164:165], 1.0 op_sel_hi:[1,0]
	v_pk_add_f32 v[166:167], v[166:167], 1.0 op_sel_hi:[1,0]
	v_pk_add_f32 v[168:169], v[168:169], 1.0 op_sel_hi:[1,0]
	v_pk_add_f32 v[170:171], v[170:171], 1.0 op_sel_hi:[1,0]
	v_rcp_f32_e32 v164, v164
	v_rcp_f32_e32 v165, v165
	v_rcp_f32_e32 v166, v166
	v_rcp_f32_e32 v167, v167
	v_rcp_f32_e32 v168, v168
	v_rcp_f32_e32 v169, v169
	v_rcp_f32_e32 v170, v170
	v_rcp_f32_e32 v171, v171
	v_pk_mul_f32 v[164:165], v[108:109], v[164:165]
	v_pk_mul_f32 v[166:167], v[110:111], v[166:167]
	v_pk_mul_f32 v[168:169], v[104:105], v[168:169]
	v_pk_mul_f32 v[170:171], v[106:107], v[170:171]
	v_pk_mul_f32 v[164:165], v[164:165], v[100:101]
	v_pk_mul_f32 v[166:167], v[166:167], v[102:103]
	v_pk_mul_f32 v[168:169], v[168:169], v[96:97]
	v_pk_mul_f32 v[170:171], v[170:171], v[98:99]
	v_cvt_pk_bf16_f32 v164, v164, v165
	v_cvt_pk_bf16_f32 v165, v166, v167
	v_cvt_pk_bf16_f32 v166, v168, v169
	v_cvt_pk_bf16_f32 v167, v170, v171
	global_store_dwordx4 v[172:173], v[164:167], off nt
	s_mov_b32 s98, 0x2c000
	v_lshl_add_u64 v[172:173], v[148:149], 0, s[98:99]
	v_pk_mul_f32 v[156:157], v[92:93], s[100:101]
	v_pk_mul_f32 v[158:159], v[94:95], s[100:101]
	v_pk_mul_f32 v[160:161], v[88:89], s[100:101]
	v_pk_mul_f32 v[162:163], v[90:91], s[100:101]
	v_exp_f32_e32 v156, v156
	v_exp_f32_e32 v157, v157
	v_exp_f32_e32 v158, v158
	v_exp_f32_e32 v159, v159
	v_exp_f32_e32 v160, v160
	v_exp_f32_e32 v161, v161
	v_exp_f32_e32 v162, v162
	v_exp_f32_e32 v163, v163
	v_pk_add_f32 v[156:157], v[156:157], 1.0 op_sel_hi:[1,0]
	v_pk_add_f32 v[158:159], v[158:159], 1.0 op_sel_hi:[1,0]
	v_pk_add_f32 v[160:161], v[160:161], 1.0 op_sel_hi:[1,0]
	v_pk_add_f32 v[162:163], v[162:163], 1.0 op_sel_hi:[1,0]
	v_rcp_f32_e32 v156, v156
	v_rcp_f32_e32 v157, v157
	v_rcp_f32_e32 v158, v158
	v_rcp_f32_e32 v159, v159
	v_rcp_f32_e32 v160, v160
	v_rcp_f32_e32 v161, v161
	v_rcp_f32_e32 v162, v162
	v_rcp_f32_e32 v163, v163
	v_pk_mul_f32 v[156:157], v[92:93], v[156:157]
	v_pk_mul_f32 v[158:159], v[94:95], v[158:159]
	v_pk_mul_f32 v[160:161], v[88:89], v[160:161]
	v_pk_mul_f32 v[162:163], v[90:91], v[162:163]
	v_pk_mul_f32 v[156:157], v[156:157], v[84:85]
	v_pk_mul_f32 v[158:159], v[158:159], v[86:87]
	v_pk_mul_f32 v[160:161], v[160:161], v[80:81]
	v_pk_mul_f32 v[162:163], v[162:163], v[82:83]
	v_cvt_pk_bf16_f32 v156, v156, v157
	v_cvt_pk_bf16_f32 v157, v158, v159
	v_cvt_pk_bf16_f32 v158, v160, v161
	v_cvt_pk_bf16_f32 v159, v162, v163
	global_store_dwordx4 v[172:173], v[156:159], off nt
	s_mov_b32 s98, 0x42000
	v_lshl_add_u64 v[172:173], v[148:149], 0, s[98:99]
	v_pk_mul_f32 v[164:165], v[76:77], s[100:101]
	v_pk_mul_f32 v[166:167], v[78:79], s[100:101]
	v_pk_mul_f32 v[168:169], v[72:73], s[100:101]
	v_pk_mul_f32 v[170:171], v[74:75], s[100:101]
	v_exp_f32_e32 v164, v164
	v_exp_f32_e32 v165, v165
	v_exp_f32_e32 v166, v166
	v_exp_f32_e32 v167, v167
	v_exp_f32_e32 v168, v168
	v_exp_f32_e32 v169, v169
	v_exp_f32_e32 v170, v170
	v_exp_f32_e32 v171, v171
	v_pk_add_f32 v[164:165], v[164:165], 1.0 op_sel_hi:[1,0]
	v_pk_add_f32 v[166:167], v[166:167], 1.0 op_sel_hi:[1,0]
	v_pk_add_f32 v[168:169], v[168:169], 1.0 op_sel_hi:[1,0]
	v_pk_add_f32 v[170:171], v[170:171], 1.0 op_sel_hi:[1,0]
	v_rcp_f32_e32 v164, v164
	v_rcp_f32_e32 v165, v165
	v_rcp_f32_e32 v166, v166
	v_rcp_f32_e32 v167, v167
	v_rcp_f32_e32 v168, v168
	v_rcp_f32_e32 v169, v169
	v_rcp_f32_e32 v170, v170
	v_rcp_f32_e32 v171, v171
	v_pk_mul_f32 v[164:165], v[76:77], v[164:165]
	v_pk_mul_f32 v[166:167], v[78:79], v[166:167]
	v_pk_mul_f32 v[168:169], v[72:73], v[168:169]
	v_pk_mul_f32 v[170:171], v[74:75], v[170:171]
	v_pk_mul_f32 v[164:165], v[164:165], v[68:69]
	v_pk_mul_f32 v[166:167], v[166:167], v[70:71]
	v_pk_mul_f32 v[168:169], v[168:169], v[64:65]
	v_pk_mul_f32 v[170:171], v[170:171], v[66:67]
	v_cvt_pk_bf16_f32 v164, v164, v165
	v_cvt_pk_bf16_f32 v165, v166, v167
	v_cvt_pk_bf16_f32 v166, v168, v169
	v_cvt_pk_bf16_f32 v167, v170, v171
	global_store_dwordx4 v[172:173], v[164:167], off nt
	s_mov_b32 s98, 0xb0000
	v_lshl_add_u64 v[172:173], v[148:149], 0, s[98:99]
	v_pk_mul_f32 v[156:157], v[60:61], s[100:101]
	v_pk_mul_f32 v[158:159], v[62:63], s[100:101]
	v_pk_mul_f32 v[160:161], v[56:57], s[100:101]
	v_pk_mul_f32 v[162:163], v[58:59], s[100:101]
	v_exp_f32_e32 v156, v156
	v_exp_f32_e32 v157, v157
	v_exp_f32_e32 v158, v158
	v_exp_f32_e32 v159, v159
	v_exp_f32_e32 v160, v160
	v_exp_f32_e32 v161, v161
	v_exp_f32_e32 v162, v162
	v_exp_f32_e32 v163, v163
	v_pk_add_f32 v[156:157], v[156:157], 1.0 op_sel_hi:[1,0]
	v_pk_add_f32 v[158:159], v[158:159], 1.0 op_sel_hi:[1,0]
	v_pk_add_f32 v[160:161], v[160:161], 1.0 op_sel_hi:[1,0]
	v_pk_add_f32 v[162:163], v[162:163], 1.0 op_sel_hi:[1,0]
	v_rcp_f32_e32 v156, v156
	v_rcp_f32_e32 v157, v157
	v_rcp_f32_e32 v158, v158
	v_rcp_f32_e32 v159, v159
	v_rcp_f32_e32 v160, v160
	v_rcp_f32_e32 v161, v161
	v_rcp_f32_e32 v162, v162
	v_rcp_f32_e32 v163, v163
	v_pk_mul_f32 v[156:157], v[60:61], v[156:157]
	v_pk_mul_f32 v[158:159], v[62:63], v[158:159]
	v_pk_mul_f32 v[160:161], v[56:57], v[160:161]
	v_pk_mul_f32 v[162:163], v[58:59], v[162:163]
	v_pk_mul_f32 v[156:157], v[156:157], v[52:53]
	v_pk_mul_f32 v[158:159], v[158:159], v[54:55]
	v_pk_mul_f32 v[160:161], v[160:161], v[48:49]
	v_pk_mul_f32 v[162:163], v[162:163], v[50:51]
	v_cvt_pk_bf16_f32 v156, v156, v157
	v_cvt_pk_bf16_f32 v157, v158, v159
	v_cvt_pk_bf16_f32 v158, v160, v161
	v_cvt_pk_bf16_f32 v159, v162, v163
	global_store_dwordx4 v[172:173], v[156:159], off nt
	s_mov_b32 s98, 0xc6000
	v_lshl_add_u64 v[172:173], v[148:149], 0, s[98:99]
	v_pk_mul_f32 v[164:165], v[44:45], s[100:101]
	v_pk_mul_f32 v[166:167], v[46:47], s[100:101]
	v_pk_mul_f32 v[168:169], v[40:41], s[100:101]
	v_pk_mul_f32 v[170:171], v[42:43], s[100:101]
	v_exp_f32_e32 v164, v164
	v_exp_f32_e32 v165, v165
	v_exp_f32_e32 v166, v166
	v_exp_f32_e32 v167, v167
	v_exp_f32_e32 v168, v168
	v_exp_f32_e32 v169, v169
	v_exp_f32_e32 v170, v170
	v_exp_f32_e32 v171, v171
	v_pk_add_f32 v[164:165], v[164:165], 1.0 op_sel_hi:[1,0]
	v_pk_add_f32 v[166:167], v[166:167], 1.0 op_sel_hi:[1,0]
	v_pk_add_f32 v[168:169], v[168:169], 1.0 op_sel_hi:[1,0]
	v_pk_add_f32 v[170:171], v[170:171], 1.0 op_sel_hi:[1,0]
	v_rcp_f32_e32 v164, v164
	v_rcp_f32_e32 v165, v165
	v_rcp_f32_e32 v166, v166
	v_rcp_f32_e32 v167, v167
	v_rcp_f32_e32 v168, v168
	v_rcp_f32_e32 v169, v169
	v_rcp_f32_e32 v170, v170
	v_rcp_f32_e32 v171, v171
	v_pk_mul_f32 v[164:165], v[44:45], v[164:165]
	v_pk_mul_f32 v[166:167], v[46:47], v[166:167]
	v_pk_mul_f32 v[168:169], v[40:41], v[168:169]
	v_pk_mul_f32 v[170:171], v[42:43], v[170:171]
	v_pk_mul_f32 v[164:165], v[164:165], v[36:37]
	v_pk_mul_f32 v[166:167], v[166:167], v[38:39]
	v_pk_mul_f32 v[168:169], v[168:169], v[32:33]
	v_pk_mul_f32 v[170:171], v[170:171], v[34:35]
	v_cvt_pk_bf16_f32 v164, v164, v165
	v_cvt_pk_bf16_f32 v165, v166, v167
	v_cvt_pk_bf16_f32 v166, v168, v169
	v_cvt_pk_bf16_f32 v167, v170, v171
	global_store_dwordx4 v[172:173], v[164:167], off nt
	s_mov_b32 s98, 0xdc000
	v_lshl_add_u64 v[172:173], v[148:149], 0, s[98:99]
	v_pk_mul_f32 v[156:157], v[28:29], s[100:101]
	v_pk_mul_f32 v[158:159], v[30:31], s[100:101]
	v_pk_mul_f32 v[160:161], v[24:25], s[100:101]
	v_pk_mul_f32 v[162:163], v[26:27], s[100:101]
	v_exp_f32_e32 v156, v156
	v_exp_f32_e32 v157, v157
	v_exp_f32_e32 v158, v158
	v_exp_f32_e32 v159, v159
	v_exp_f32_e32 v160, v160
	v_exp_f32_e32 v161, v161
	v_exp_f32_e32 v162, v162
	v_exp_f32_e32 v163, v163
	v_pk_add_f32 v[156:157], v[156:157], 1.0 op_sel_hi:[1,0]
	v_pk_add_f32 v[158:159], v[158:159], 1.0 op_sel_hi:[1,0]
	v_pk_add_f32 v[160:161], v[160:161], 1.0 op_sel_hi:[1,0]
	v_pk_add_f32 v[162:163], v[162:163], 1.0 op_sel_hi:[1,0]
	v_rcp_f32_e32 v156, v156
	v_rcp_f32_e32 v157, v157
	v_rcp_f32_e32 v158, v158
	v_rcp_f32_e32 v159, v159
	v_rcp_f32_e32 v160, v160
	v_rcp_f32_e32 v161, v161
	v_rcp_f32_e32 v162, v162
	v_rcp_f32_e32 v163, v163
	v_pk_mul_f32 v[156:157], v[28:29], v[156:157]
	v_pk_mul_f32 v[158:159], v[30:31], v[158:159]
	v_pk_mul_f32 v[160:161], v[24:25], v[160:161]
	v_pk_mul_f32 v[162:163], v[26:27], v[162:163]
	v_pk_mul_f32 v[156:157], v[156:157], v[20:21]
	v_pk_mul_f32 v[158:159], v[158:159], v[22:23]
	v_pk_mul_f32 v[160:161], v[160:161], v[16:17]
	v_pk_mul_f32 v[162:163], v[162:163], v[18:19]
	v_cvt_pk_bf16_f32 v156, v156, v157
	v_cvt_pk_bf16_f32 v157, v158, v159
	v_cvt_pk_bf16_f32 v158, v160, v161
	v_cvt_pk_bf16_f32 v159, v162, v163
	global_store_dwordx4 v[172:173], v[156:159], off nt
	s_mov_b32 s98, 0xf2000
	v_lshl_add_u64 v[172:173], v[148:149], 0, s[98:99]
	v_pk_mul_f32 v[164:165], v[12:13], s[100:101]
	v_pk_mul_f32 v[166:167], v[14:15], s[100:101]
	v_pk_mul_f32 v[168:169], v[8:9], s[100:101]
	v_pk_mul_f32 v[170:171], v[10:11], s[100:101]
	v_exp_f32_e32 v164, v164
	v_exp_f32_e32 v165, v165
	v_exp_f32_e32 v166, v166
	v_exp_f32_e32 v167, v167
	v_exp_f32_e32 v168, v168
	v_exp_f32_e32 v169, v169
	v_exp_f32_e32 v170, v170
	v_exp_f32_e32 v171, v171
	v_pk_add_f32 v[164:165], v[164:165], 1.0 op_sel_hi:[1,0]
	v_pk_add_f32 v[166:167], v[166:167], 1.0 op_sel_hi:[1,0]
	v_pk_add_f32 v[168:169], v[168:169], 1.0 op_sel_hi:[1,0]
	v_pk_add_f32 v[170:171], v[170:171], 1.0 op_sel_hi:[1,0]
	v_rcp_f32_e32 v164, v164
	v_rcp_f32_e32 v165, v165
	v_rcp_f32_e32 v166, v166
	v_rcp_f32_e32 v167, v167
	v_rcp_f32_e32 v168, v168
	v_rcp_f32_e32 v169, v169
	v_rcp_f32_e32 v170, v170
	v_rcp_f32_e32 v171, v171
	v_pk_mul_f32 v[164:165], v[12:13], v[164:165]
	v_pk_mul_f32 v[166:167], v[14:15], v[166:167]
	v_pk_mul_f32 v[168:169], v[8:9], v[168:169]
	v_pk_mul_f32 v[170:171], v[10:11], v[170:171]
	v_pk_mul_f32 v[164:165], v[164:165], v[4:5]
	v_pk_mul_f32 v[166:167], v[166:167], v[6:7]
	v_pk_mul_f32 v[168:169], v[168:169], v[0:1]
	v_pk_mul_f32 v[170:171], v[170:171], v[2:3]
	v_cvt_pk_bf16_f32 v164, v164, v165
	v_cvt_pk_bf16_f32 v165, v166, v167
	v_cvt_pk_bf16_f32 v166, v168, v169
	v_cvt_pk_bf16_f32 v167, v170, v171
	global_store_dwordx4 v[172:173], v[164:167], off nt
	s_andn2_b64 vcc, exec, s[0:1]
	s_mov_b64 s[0:1], -1
	s_cbranch_vccnz .LBB0_1097
	s_andn2_b64 vcc, exec, s[8:9]
	s_cbranch_vccnz .LBB0_1096
	s_barrier
	s_branch .LBB0_1096
